# stack: nt in-proj output stores + norm2 x-load hoist + out-proj un-permuted B staging (64B-contiguous f32 epilogue rows)
# speedup vs baseline: 1.0042x; 1.0042x over previous
.LBB0_69:
	s_or_b64 exec, exec, s[20:21]
	v_ashrrev_i32_e32 v1, 31, v0
	v_and_b32_e32 v5, v7, v16
	v_cndmask_b32_e64 v7, v1, 0, vcc
	v_cndmask_b32_e64 v6, v0, 32, vcc
	v_lshlrev_b64 v[0:1], v4, v[0:1]
	v_lshlrev_b32_e32 v176, 12, v5
	v_lshl_add_u64 v[0:1], v[2:3], 0, v[0:1]
	v_lshl_add_u64 v[0:1], v[0:1], 0, v[176:177]
	v_readlane_b32 s0, v253, 0
	v_mov_b32_e32 v23, v177
	v_readlane_b32 s1, v253, 1
	v_lshl_add_u64 v[0:1], v[0:1], 0, v[22:23]
	s_load_dwordx16 s[4:19], s[0:1], 0xf0
	global_load_dwordx4 v[12:15], v[0:1], off nt
	global_load_dwordx4 v[8:11], v[0:1], off offset:16 nt
	global_load_dwordx4 v[56:59], v[0:1], off offset:2048 nt
	global_load_dwordx4 v[60:63], v[0:1], off offset:2064 nt
	v_lshl_add_u64 v[2:3], v[6:7], 0, s[48:49]
	s_waitcnt lgkmcnt(0)
	s_movk_i32 s4, 0x6000
	s_mov_b64 s[40:41], 0x4000
	v_mov_b64_e32 v[4:5], s[6:7]
	v_mad_u64_u32 v[30:31], s[0:1], v2, s4, v[4:5]
	v_mov_b32_e32 v2, v31
	v_mad_u64_u32 v[2:3], s[0:1], v3, s4, v[2:3]
	v_mov_b32_e32 v31, v2
	s_mov_b64 s[0:1], 0x3000
	v_and_b32_e32 v25, 64, v199
	v_add_u32_e32 v25, 64, v25
	s_movk_i32 s92, 0x6000
	s_waitcnt vmcnt(2)
	v_mov_b32_e32 v4, v13
	v_mov_b32_e32 v5, v9
	v_mov_b32_e32 v2, v12
	v_mov_b32_e32 v3, v8
	v_pk_mul_f32 v[4:5], v[4:5], v[4:5]
	s_nop 0
	v_pk_fma_f32 v[2:3], v[2:3], v[2:3], v[4:5]
	v_mov_b32_e32 v4, v14
	v_mov_b32_e32 v5, v10
	v_pk_fma_f32 v[2:3], v[4:5], v[4:5], v[2:3]
	v_mov_b32_e32 v4, v15
	v_mov_b32_e32 v5, v11
	v_pk_fma_f32 v[26:27], v[4:5], v[4:5], v[2:3]
	s_waitcnt vmcnt(1)
	v_mov_b32_e32 v4, v56
	v_mov_b32_e32 v5, v57
	v_mov_b32_e32 v6, v58
	v_mov_b32_e32 v7, v59
	s_waitcnt vmcnt(0)
	v_mov_b32_e32 v0, v60
	v_mov_b32_e32 v1, v61
	v_mov_b32_e32 v2, v62
	v_mov_b32_e32 v3, v63
	v_add_f32_e32 v17, v26, v27
	v_xor_b32_e32 v26, 32, v199
	v_cmp_lt_i32_e32 vcc, v26, v25
	s_waitcnt vmcnt(1)
	v_mov_b32_e32 v32, v5
	s_waitcnt vmcnt(0)
	v_mov_b32_e32 v33, v1
	v_mov_b32_e32 v28, v4
	v_mov_b32_e32 v29, v0
	v_pk_mul_f32 v[32:33], v[32:33], v[32:33]
	v_cndmask_b32_e32 v26, v199, v26, vcc
	v_pk_fma_f32 v[28:29], v[28:29], v[28:29], v[32:33]
	v_mov_b32_e32 v32, v6
	v_mov_b32_e32 v33, v2
	v_pk_fma_f32 v[28:29], v[32:33], v[32:33], v[28:29]
	v_mov_b32_e32 v32, v7
	v_mov_b32_e32 v33, v3
	v_pk_fma_f32 v[28:29], v[32:33], v[32:33], v[28:29]
	v_lshlrev_b32_e32 v26, 2, v26
	v_add_f32_e32 v17, v17, v28
	v_add_f32_e32 v17, v17, v29
	v_lshl_add_u64 v[28:29], v[30:31], 0, s[0:1]
	v_lshl_add_u64 v[30:31], v[30:31], 0, s[40:41]
	v_lshl_add_u64 v[36:37], v[28:29], 0, v[22:23]
	v_lshl_add_u64 v[44:45], v[30:31], 0, v[22:23]
	global_load_dwordx4 v[32:35], v[36:37], off offset:16
	s_nop 0
	global_load_dwordx4 v[36:39], v[36:37], off
	s_nop 0
	global_load_dwordx4 v[40:43], v[44:45], off offset:16
	s_nop 0
	global_load_dwordx4 v[44:47], v[44:45], off
	ds_bpermute_b32 v26, v26, v17
	s_mov_b32 s0, 0x800000
	s_waitcnt lgkmcnt(0)
	v_add_f32_e32 v17, v17, v26
	v_xor_b32_e32 v26, 16, v199
	v_cmp_lt_i32_e32 vcc, v26, v25
	s_waitcnt vmcnt(0)
	v_pk_add_f32 v[54:55], v[46:47], 1.0 op_sel_hi:[1,0]
	global_load_dwordx4 v[46:49], v[18:19], off offset:16
	global_load_dwordx4 v[50:53], v[18:19], off
	v_cndmask_b32_e32 v26, v199, v26, vcc
	v_lshlrev_b32_e32 v26, 2, v26
	ds_bpermute_b32 v26, v26, v17
	s_waitcnt lgkmcnt(0)
	v_add_f32_e32 v17, v17, v26
	v_xor_b32_e32 v26, 8, v199
	v_cmp_lt_i32_e32 vcc, v26, v25
	s_nop 1
	v_cndmask_b32_e32 v26, v199, v26, vcc
	v_lshlrev_b32_e32 v26, 2, v26
	ds_bpermute_b32 v26, v26, v17
	s_waitcnt lgkmcnt(0)
	v_add_f32_e32 v17, v17, v26
	v_xor_b32_e32 v26, 4, v199
	v_cmp_lt_i32_e32 vcc, v26, v25
	s_nop 1
	v_cndmask_b32_e32 v26, v199, v26, vcc
	v_lshlrev_b32_e32 v26, 2, v26
	ds_bpermute_b32 v26, v26, v17
	s_waitcnt lgkmcnt(0)
	v_add_f32_e32 v17, v17, v26
	v_xor_b32_e32 v26, 2, v199
	v_cmp_lt_i32_e32 vcc, v26, v25
	s_nop 1
	v_cndmask_b32_e32 v26, v199, v26, vcc
	v_lshlrev_b32_e32 v26, 2, v26
	ds_bpermute_b32 v26, v26, v17
	s_waitcnt lgkmcnt(0)
	v_add_f32_e32 v17, v17, v26
	v_xor_b32_e32 v26, 1, v199
	v_cmp_lt_i32_e32 vcc, v26, v25
	s_nop 1
	v_cndmask_b32_e32 v25, v199, v26, vcc
	v_lshlrev_b32_e32 v25, 2, v25
	ds_bpermute_b32 v25, v25, v17
	s_waitcnt lgkmcnt(0)
	v_add_f32_e32 v17, v17, v25
	v_fmamk_f32 v17, v17, 0x3a800000, v194
	v_cmp_gt_f32_e32 vcc, s0, v17
	v_mul_f32_e32 v25, 0x4b800000, v17
	s_nop 0
	v_cndmask_b32_e32 v17, v17, v25, vcc
	v_rsq_f32_e32 v17, v17
	s_nop 0
	v_mul_f32_e32 v25, 0x45800000, v17
	v_cndmask_b32_e32 v26, v17, v25, vcc
	v_pk_mul_f32 v[14:15], v[14:15], v[26:27] op_sel_hi:[1,0]
	v_pk_mul_f32 v[12:13], v[12:13], v[26:27] op_sel_hi:[1,0]
	v_pk_mul_f32 v[8:9], v[8:9], v[26:27] op_sel_hi:[1,0]
	v_pk_mul_f32 v[10:11], v[10:11], v[26:27] op_sel_hi:[1,0]
	v_mov_b32_e32 v25, v177
	v_pk_mul_f32 v[6:7], v[6:7], v[26:27] op_sel_hi:[1,0]
	v_pk_mul_f32 v[4:5], v[4:5], v[26:27] op_sel_hi:[1,0]
	v_pk_mul_f32 v[0:1], v[0:1], v[26:27] op_sel_hi:[1,0]
	v_pk_mul_f32 v[2:3], v[2:3], v[26:27] op_sel_hi:[1,0]
	s_waitcnt vmcnt(1)
	v_pk_mul_f32 v[8:9], v[8:9], v[46:47]
	s_waitcnt vmcnt(0)
	v_pk_mul_f32 v[14:15], v[52:53], v[14:15]
	v_pk_mul_f32 v[12:13], v[50:51], v[12:13]
	v_pk_fma_f32 v[14:15], v[54:55], v[14:15], v[38:39]
	v_pk_add_f32 v[38:39], v[44:45], 1.0 op_sel_hi:[1,0]
	v_pk_mul_f32 v[10:11], v[10:11], v[48:49]
	v_pk_fma_f32 v[12:13], v[38:39], v[12:13], v[36:37]
	s_nop 0
	v_cvt_pk_bf16_f32 v12, v12, v13
	v_cvt_pk_bf16_f32 v13, v14, v15
	v_pk_add_f32 v[14:15], v[40:41], 1.0 op_sel_hi:[1,0]
	s_nop 0
	v_pk_fma_f32 v[8:9], v[14:15], v[8:9], v[32:33]
	v_lshl_add_u64 v[32:33], v[30:31], 0, v[24:25]
	v_cvt_pk_bf16_f32 v14, v8, v9
	v_pk_add_f32 v[8:9], v[42:43], 1.0 op_sel_hi:[1,0]
	s_nop 0
	v_pk_fma_f32 v[8:9], v[8:9], v[10:11], v[34:35]
	s_nop 0
	v_cvt_pk_bf16_f32 v15, v8, v9
	global_store_dwordx4 v[20:21], v[12:15], off offset:-1024
	s_nop 1
	v_lshl_add_u64 v[12:13], v[28:29], 0, v[24:25]
	global_load_dwordx4 v[8:11], v[12:13], off offset:16
	s_nop 0
	global_load_dwordx4 v[12:15], v[12:13], off
	s_nop 0
	global_load_dwordx4 v[28:31], v[32:33], off offset:16
	s_nop 0
	global_load_dwordx4 v[32:35], v[32:33], off
	s_waitcnt vmcnt(0)
	v_pk_add_f32 v[42:43], v[34:35], 1.0 op_sel_hi:[1,0]
	global_load_dwordx4 v[34:37], v[18:19], off offset:2064
	global_load_dwordx4 v[38:41], v[18:19], off offset:2048
	s_waitcnt vmcnt(1)
	v_pk_mul_f32 v[0:1], v[0:1], v[34:35]
	s_waitcnt vmcnt(0)
	v_pk_mul_f32 v[6:7], v[6:7], v[40:41]
	v_pk_mul_f32 v[4:5], v[4:5], v[38:39]
	v_pk_fma_f32 v[6:7], v[42:43], v[6:7], v[14:15]
	v_pk_add_f32 v[14:15], v[32:33], 1.0 op_sel_hi:[1,0]
	v_pk_mul_f32 v[2:3], v[2:3], v[36:37]
	v_pk_fma_f32 v[4:5], v[14:15], v[4:5], v[12:13]
	s_nop 0
	v_cvt_pk_bf16_f32 v4, v4, v5
	v_cvt_pk_bf16_f32 v5, v6, v7
	v_pk_add_f32 v[6:7], v[28:29], 1.0 op_sel_hi:[1,0]
	s_nop 0
	v_pk_fma_f32 v[0:1], v[6:7], v[0:1], v[8:9]
	s_nop 0
	v_cvt_pk_bf16_f32 v6, v0, v1
	v_pk_add_f32 v[0:1], v[30:31], 1.0 op_sel_hi:[1,0]
	s_nop 0
	v_pk_fma_f32 v[0:1], v[0:1], v[2:3], v[10:11]
	s_nop 0
	v_cvt_pk_bf16_f32 v7, v0, v1
	global_store_dwordx4 v[20:21], v[4:7], off

.LBB0_93:
	s_andn2_b64 vcc, exec, s[48:49]
	s_cbranch_vccnz .LBB0_132
	v_ashrrev_i32_e32 v1, 31, v8
	v_lshrrev_b32_e32 v1, 26, v1
	v_add_u32_e32 v1, v8, v1
	v_ashrrev_i32_e32 v9, 6, v1
	v_bfe_i32 v1, v8, 27, 1
	v_lshlrev_b32_e32 v0, 4, v8
	v_lshrrev_b32_e32 v1, 22, v1
	v_add_u32_e32 v1, v0, v1
	v_and_b32_e32 v1, 0xfffffc00, v1
	v_sub_u32_e32 v1, v0, v1
	v_add_u32_e32 v0, 0x2000, v0
	v_ashrrev_i32_e32 v5, 31, v0
	v_lshrrev_b32_e32 v5, 22, v5
	v_add_u32_e32 v5, v0, v5
	v_ashrrev_i32_e32 v12, 10, v5
	s_waitcnt vmcnt(0)
	v_lshrrev_b32_e32 v2, 4, v1
	v_mul_i32_i24_e32 v5, 0x400, v12
	v_bitop3_b32 v2, v2, v1, 32 bitop3:0x6c
	v_ashrrev_i32_e32 v1, 31, v1
	v_sub_u32_e32 v0, v0, v5
	v_lshrrev_b32_e32 v1, 26, v1
	v_lshrrev_b32_e32 v5, 4, v0
	v_add_u32_e32 v1, v2, v1
	v_bitop3_b32 v0, v5, v0, 32 bitop3:0x6c
	v_ashrrev_i32_e32 v10, 6, v1
	v_ashrrev_i32_e32 v6, 31, v0
	v_lshlrev_b32_e32 v3, 3, v9
	v_mul_i32_i24_e32 v4, 64, v10
	v_lshrrev_b32_e32 v6, 26, v6
	v_and_b32_e32 v3, -16, v3
	v_sub_u32_e32 v2, v2, v4
	v_add_u32_e32 v6, v0, v6
	v_add_u32_e32 v1, v10, v3
	v_ashrrev_i16_sdwa v2, v197, sext(v2) dst_sel:DWORD dst_unused:UNUSED_PAD src0_sel:DWORD src1_sel:BYTE_0
	v_lshlrev_b32_e32 v5, 3, v12
	v_ashrrev_i32_e32 v13, 6, v6
	v_and_b32_e32 v6, 0xc0, v6
	s_ashr_i32 s21, s30, 6
	v_lshlrev_b32_e32 v3, 5, v9
	v_bfe_i32 v11, v2, 0, 16
	v_lshlrev_b32_e32 v2, 1, v1
	v_lshrrev_b32_e32 v4, 2, v1
	v_and_b32_e32 v5, -16, v5
	v_sub_u32_e32 v0, v0, v6
	s_lshl_b32 s35, s21, 10
	v_and_b32_e32 v2, 0xc0, v2
	v_add_u32_e32 v5, v13, v5
	v_ashrrev_i16_sdwa v0, v197, sext(v0) dst_sel:DWORD dst_unused:UNUSED_PAD src0_sel:DWORD src1_sel:BYTE_0
	v_and_b32_e32 v3, 32, v3
	v_and_b32_e32 v16, 3, v10
	v_and_b32_e32 v4, 4, v4
	v_lshlrev_b32_e32 v7, 5, v12
	v_bfe_i32 v14, v0, 0, 16
	v_lshlrev_b32_e32 v0, 1, v5
	v_lshrrev_b32_e32 v6, 2, v5
	v_add_lshl_u32 v3, v3, v11, 1
	v_and_b32_e32 v4, 31, v1
	v_or_b32_e32 v2, v2, v4
	s_add_i32 s66, s35, 0
	v_and_b32_e32 v0, 0xc0, v0
	v_and_b32_e32 v7, 32, v7
	v_and_b32_e32 v15, 3, v13
	v_and_b32_e32 v6, 4, v6
	v_lshl_add_u32 v140, v2, 11, v3
	s_add_i32 m0, s66, 0x10000
	s_ashr_i32 s20, s30, 8
	v_add_lshl_u32 v7, v7, v14, 1
	v_and_b32_e32 v6, 31, v5
	v_or_b32_e32 v0, v0, v6
	global_load_lds_dwordx4 v140, s[46:47]
	s_add_i32 m0, s66, 0x12000
	v_lshl_add_u32 v136, v0, 11, v7
	s_add_u32 s48, s46, 0x10000
	global_load_lds_dwordx4 v136, s[46:47]
	s_addc_u32 s49, s47, 0
	s_add_i32 m0, s66, 0x14000
	s_add_i32 s67, s66, 0x2000
	global_load_lds_dwordx4 v140, s[48:49]
	s_add_i32 m0, s66, 0x16000
	v_lshl_add_u32 v142, v1, 11, v3
	global_load_lds_dwordx4 v136, s[48:49]
	s_mov_b32 m0, s66
	s_add_u32 s48, s44, 0x40000
	v_lshl_add_u32 v138, v5, 11, v7
	global_load_lds_dwordx4 v142, s[44:45]
	s_mov_b32 m0, s67
	s_addc_u32 s49, s45, 0
	s_add_i32 s68, s66, 0x4000
	global_load_lds_dwordx4 v138, s[44:45]
	s_mov_b32 m0, s68
	s_add_i32 s69, s66, 0x6000
	global_load_lds_dwordx4 v142, s[48:49]
	s_mov_b32 m0, s69
	s_cmp_eq_u32 s20, 1
	global_load_lds_dwordx4 v138, s[48:49]
	v_mov_b32_e32 v141, v177
	v_mov_b32_e32 v137, v177
	v_mov_b32_e32 v143, v177
	v_mov_b32_e32 v139, v177
	s_cselect_b64 s[4:5], -1, 0
	v_lshl_add_u64 v[4:5], s[46:47], 0, v[140:141]
	v_lshl_add_u64 v[2:3], s[46:47], 0, v[136:137]
	v_lshl_add_u64 v[0:1], s[44:45], 0, v[142:143]
	v_writelane_b32 v252, s4, 32
	s_cmp_lg_u32 s20, 1
	v_lshl_add_u64 v[6:7], s[44:45], 0, v[138:139]
	v_writelane_b32 v252, s5, 33
	s_cbranch_scc1 .LBB0_96
	s_barrier
.LBB0_96:
	s_and_b32 s0, s21, 3
	s_add_i32 m0, s66, 0x18000
	v_lshl_add_u64 v[4:5], v[4:5], 0, s[26:27]
	s_lshl_b32 s21, s20, 13
	s_lshl_b32 s37, s0, 12
	s_waitcnt vmcnt(2)
	s_barrier
	global_load_lds_dwordx4 v[4:5], off
	v_lshl_add_u64 v[2:3], v[2:3], 0, s[26:27]
	s_add_i32 m0, s66, 0x1a000
	s_add_i32 s48, s66, 0x8000
	s_add_i32 s49, s66, 0xa000
	global_load_lds_dwordx4 v[2:3], off
	v_lshl_add_u64 v[0:1], v[0:1], 0, s[26:27]
	s_mov_b32 m0, s48
	s_add_u32 s50, s46, 0x10080
	global_load_lds_dwordx4 v[0:1], off
	v_lshl_add_u64 v[0:1], v[6:7], 0, s[26:27]
	s_mov_b32 m0, s49
	s_addc_u32 s51, s47, 0
	global_load_lds_dwordx4 v[0:1], off
	s_add_i32 m0, s66, 0x1c000
	v_lshl_add_u64 v[0:1], s[50:51], 0, v[140:141]
	global_load_lds_dwordx4 v[0:1], off
	v_lshl_add_u64 v[0:1], s[50:51], 0, v[136:137]
	s_add_i32 m0, s66, 0x1e000
	v_lshrrev_b32_e32 v2, 1, v8
	global_load_lds_dwordx4 v[0:1], off
	v_and_b32_e32 v1, 15, v8
	v_and_b32_e32 v2, 24, v2
	v_lshl_or_b32 v0, s20, 6, v1
	v_lshlrev_b32_e32 v3, 2, v8
	v_lshlrev_b32_e32 v4, 1, v2
	v_and_b32_e32 v3, 32, v3
	v_lshl_or_b32 v1, v1, 6, v4
	v_or_b32_e32 v4, 16, v0
	v_bitop3_b32 v6, v1, s21, v3 bitop3:0xde
	v_bitop3_b32 v180, v1, s37, v3 bitop3:0xde
	v_ashrrev_i32_e32 v1, 31, v0
	v_ashrrev_i32_e32 v5, 31, v4
	v_lshlrev_b64 v[144:145], 12, v[0:1]
	v_lshlrev_b64 v[148:149], 12, v[4:5]
	v_or_b32_e32 v4, 32, v0
	v_or_b32_e32 v0, 48, v0
	s_cmpk_lt_u32 s30, 0x100
	v_readlane_b32 s20, v253, 6
	v_ashrrev_i32_e32 v1, 31, v0
	s_cselect_b64 s[4:5], -1, 0
	s_add_i32 s20, s20, 9
	v_lshlrev_b64 v[152:153], 12, v[0:1]
	v_lshlrev_b32_e32 v0, 14, v9
	v_writelane_b32 v252, s4, 28
	s_cmp_lt_u32 s20, 21
	v_and_b32_e32 v0, 0xffff8000, v0
	v_writelane_b32 v252, s5, 29
	s_cselect_b64 s[4:5], -1, 0
	v_lshl_add_u32 v0, v10, 11, v0
	v_and_b32_e32 v1, 1, v9
	v_writelane_b32 v252, s4, 26
	v_lshl_or_b32 v0, v1, 6, v0
	v_lshl_add_u32 v160, v11, 1, v0
	v_writelane_b32 v252, s5, 27
	s_mov_b64 s[4:5], 0x80000
	v_lshlrev_b32_e32 v0, 14, v12
	v_lshl_add_u64 v[146:147], v[144:145], 0, s[4:5]
	s_mov_b64 s[4:5], 0x90000
	v_and_b32_e32 v0, 0xffff8000, v0
	s_waitcnt vmcnt(6)
	v_lshl_add_u64 v[154:155], v[144:145], 0, s[4:5]
	s_mov_b64 s[4:5], 0xa0000
	v_lshl_add_u32 v0, v13, 11, v0
	v_and_b32_e32 v1, 1, v12
	v_lshrrev_b32_e32 v2, 1, v2
	v_lshl_or_b32 v2, s0, 6, v2
	v_ashrrev_i32_e32 v5, 31, v4
	v_lshl_add_u64 v[156:157], v[144:145], 0, s[4:5]
	s_mov_b64 s[4:5], 0xb0000
	v_lshl_or_b32 v0, v1, 6, v0
	v_lshlrev_b64 v[150:151], 12, v[4:5]
	v_lshl_add_u64 v[158:159], v[144:145], 0, s[4:5]
	v_mov_b32_e32 v161, v177
	v_lshl_add_u32 v162, v14, 1, v0
	v_mov_b32_e32 v163, v177
	s_mov_b32 s50, 0
	v_add_u32_e32 v181, 0, v6
	v_lshlrev_b32_e32 v176, 2, v2
	s_barrier
	v_readlane_b32 s21, v253, 7
	s_branch .LBB0_99

.LBB0_128:
	v_readlane_b32 s4, v252, 26
	v_readlane_b32 s5, v252, 27
	s_and_b64 s[52:53], s[4:5], exec
	s_cselect_b32 s0, s61, s63
	s_cselect_b32 s37, s60, s62
	v_readlane_b32 s60, v253, 0
	v_readlane_b32 s4, v252, 19
	v_readlane_b32 s61, v253, 1
	s_add_u32 s52, s60, s37
	v_readlane_b32 s5, v252, 20
	s_addc_u32 s53, s61, s0
	s_mul_i32 s0, s4, 33
	s_mul_hi_i32 s37, s4, 33
	s_load_dwordx16 s[4:19], s[60:61], 0xf0
	s_add_u32 s0, s56, s0
	s_addc_u32 s37, s57, s37
	s_mulk_i32 s37, 0x6000
	s_mul_hi_u32 s39, s0, 0x6000
	s_add_i32 s39, s39, s37
	s_mulk_i32 s0, 0x6000
	s_waitcnt lgkmcnt(0)
	s_add_u32 s0, s6, s0
	s_addc_u32 s37, s7, s39
	s_lshl_b32 s56, s30, 8
	s_load_dwordx2 s[52:53], s[52:53], 0x0
	s_ashr_i32 s57, s56, 31
	s_lshl_b64 s[56:57], s[56:57], 2
	s_add_u32 s60, s0, s56
	s_addc_u32 s61, s37, s57
	s_lshl_b64 s[20:21], s[20:21], 2
	s_load_dwordx2 s[58:59], s[58:59], 0x0
	s_waitcnt lgkmcnt(0)
	s_add_u32 s0, s52, s20
	s_addc_u32 s30, s53, s21
	s_add_u32 s52, s0, s56
	s_addc_u32 s53, s30, s57
	s_add_u32 s0, s58, s20
	s_addc_u32 s21, s59, s21
	s_add_u32 s20, s0, s56
	s_addc_u32 s21, s21, s57
	v_lshl_add_u64 v[128:129], s[60:61], 0, v[176:177]
	s_mov_b64 s[56:57], 0x2000
	v_lshl_add_u64 v[164:165], v[128:129], 0, s[56:57]
	v_lshl_add_u64 v[178:179], s[52:53], 0, v[176:177]
	v_add_co_u32_e32 v128, vcc, s38, v128
	v_lshl_add_u64 v[166:167], v[178:179], 0, v[144:145]
	v_lshl_add_u64 v[168:169], v[178:179], 0, v[148:149]
	v_lshl_add_u64 v[170:171], v[178:179], 0, v[150:151]
	v_lshl_add_u64 v[172:173], v[178:179], 0, v[152:153]
	v_addc_co_u32_e32 v129, vcc, 0, v129, vcc
	global_load_dwordx4 v[182:185], v[166:167], off offset:64
	global_load_dwordx4 v[186:189], v[166:167], off
	global_load_dwordx4 v[208:211], v[168:169], off offset:64
	global_load_dwordx4 v[212:215], v[168:169], off
	global_load_dwordx4 v[216:219], v[170:171], off offset:64
	global_load_dwordx4 v[220:223], v[170:171], off
	global_load_dwordx4 v[224:227], v[172:173], off offset:64
	global_load_dwordx4 v[228:231], v[172:173], off
	s_nop 0
	global_load_dwordx4 v[128:131], v[128:129], off
	s_nop 0
	global_load_dwordx4 v[132:135], v[164:165], off offset:64
	v_lshl_add_u64 v[174:175], s[20:21], 0, v[176:177]
	s_mov_b64 s[56:57], -1
	s_andn2_b64 vcc, exec, s[54:55]
	s_waitcnt vmcnt(0)
	v_pk_fma_f32 v[126:127], v[126:127], v[130:131], v[188:189]
	v_pk_fma_f32 v[124:125], v[124:125], v[128:129], v[186:187]
	v_pk_fma_f32 v[184:185], v[122:123], v[134:135], v[184:185]
	v_pk_fma_f32 v[182:183], v[120:121], v[132:133], v[182:183]
	v_lshl_add_u64 v[120:121], v[174:175], 0, v[144:145]
	v_pk_fma_f32 v[118:119], v[118:119], v[130:131], v[214:215]
	v_pk_fma_f32 v[116:117], v[116:117], v[128:129], v[212:213]
	v_pk_fma_f32 v[122:123], v[112:113], v[132:133], v[208:209]
	v_lshl_add_u64 v[112:113], v[174:175], 0, v[148:149]
	global_store_dwordx4 v[120:121], v[124:127], off
	global_store_dwordx4 v[120:121], v[182:185], off offset:64
	v_pk_fma_f32 v[110:111], v[110:111], v[130:131], v[222:223]
	v_pk_fma_f32 v[124:125], v[114:115], v[134:135], v[210:211]
	global_store_dwordx4 v[112:113], v[116:119], off
	global_store_dwordx4 v[112:113], v[122:125], off offset:64
	v_pk_fma_f32 v[108:109], v[108:109], v[128:129], v[220:221]
	v_pk_fma_f32 v[116:117], v[106:107], v[134:135], v[218:219]
	v_pk_fma_f32 v[114:115], v[104:105], v[132:133], v[216:217]
	v_lshl_add_u64 v[104:105], v[174:175], 0, v[150:151]
	v_pk_fma_f32 v[102:103], v[102:103], v[130:131], v[230:231]
	v_pk_fma_f32 v[100:101], v[100:101], v[128:129], v[228:229]
	v_pk_fma_f32 v[106:107], v[96:97], v[132:133], v[224:225]
	v_lshl_add_u64 v[96:97], v[174:175], 0, v[152:153]
	global_store_dwordx4 v[104:105], v[108:111], off
	global_store_dwordx4 v[104:105], v[114:117], off offset:64
	s_nop 0
	v_pk_fma_f32 v[108:109], v[98:99], v[134:135], v[226:227]
	global_store_dwordx4 v[96:97], v[100:103], off
	global_store_dwordx4 v[96:97], v[106:109], off offset:64
	v_lshl_add_u64 v[98:99], v[178:179], 0, v[146:147]
	global_load_dwordx4 v[108:111], v[98:99], off offset:64
	global_load_dwordx4 v[114:117], v[98:99], off
	v_lshl_add_u64 v[100:101], v[178:179], 0, v[154:155]
	v_lshl_add_u64 v[102:103], v[178:179], 0, v[156:157]
	global_load_dwordx4 v[122:125], v[100:101], off offset:64
	global_load_dwordx4 v[182:185], v[100:101], off
	global_load_dwordx4 v[186:189], v[102:103], off offset:64
	global_load_dwordx4 v[208:211], v[102:103], off
	v_lshl_add_u64 v[106:107], v[178:179], 0, v[158:159]
	global_load_dwordx4 v[212:215], v[106:107], off offset:64
	global_load_dwordx4 v[216:219], v[106:107], off
	s_waitcnt vmcnt(7)
	v_pk_fma_f32 v[108:109], v[88:89], v[132:133], v[108:109]
	s_waitcnt vmcnt(6)
	v_pk_fma_f32 v[94:95], v[94:95], v[130:131], v[116:117]
	v_pk_fma_f32 v[92:93], v[92:93], v[128:129], v[114:115]
	v_lshl_add_u64 v[88:89], v[174:175], 0, v[146:147]
	v_pk_fma_f32 v[110:111], v[90:91], v[134:135], v[110:111]
	global_store_dwordx4 v[88:89], v[92:95], off
	global_store_dwordx4 v[88:89], v[108:111], off offset:64
	s_waitcnt vmcnt(6)
	v_pk_fma_f32 v[86:87], v[86:87], v[130:131], v[184:185]
	v_pk_fma_f32 v[84:85], v[84:85], v[128:129], v[182:183]
	v_pk_fma_f32 v[92:93], v[82:83], v[134:135], v[124:125]
	v_pk_fma_f32 v[90:91], v[80:81], v[132:133], v[122:123]
	v_lshl_add_u64 v[80:81], v[174:175], 0, v[154:155]
	s_waitcnt vmcnt(4)
	v_pk_fma_f32 v[78:79], v[78:79], v[130:131], v[210:211]
	v_pk_fma_f32 v[76:77], v[76:77], v[128:129], v[208:209]
	v_pk_fma_f32 v[82:83], v[72:73], v[132:133], v[186:187]
	v_lshl_add_u64 v[72:73], v[174:175], 0, v[156:157]
	global_store_dwordx4 v[80:81], v[84:87], off
	global_store_dwordx4 v[80:81], v[90:93], off offset:64
	s_waitcnt vmcnt(5)
	v_pk_fma_f32 v[66:67], v[66:67], v[134:135], v[214:215]
	v_pk_fma_f32 v[84:85], v[74:75], v[134:135], v[188:189]
	global_store_dwordx4 v[72:73], v[76:79], off
	global_store_dwordx4 v[72:73], v[82:85], off offset:64
	s_waitcnt vmcnt(6)
	v_pk_fma_f32 v[74:75], v[68:69], v[128:129], v[216:217]
	v_pk_fma_f32 v[76:77], v[70:71], v[130:131], v[218:219]
	v_lshl_add_u64 v[68:69], v[174:175], 0, v[158:159]
	v_pk_fma_f32 v[64:65], v[64:65], v[132:133], v[212:213]
	global_store_dwordx4 v[68:69], v[74:77], off
	global_store_dwordx4 v[68:69], v[64:67], off offset:64
	global_load_dwordx4 v[74:77], v[166:167], off offset:192
	s_nop 0
	global_load_dwordx4 v[82:85], v[166:167], off offset:128
	global_load_dwordx4 v[90:93], v[168:169], off offset:192
	global_load_dwordx4 v[108:111], v[168:169], off offset:128
	global_load_dwordx4 v[114:117], v[170:171], off offset:192
	global_load_dwordx4 v[122:125], v[170:171], off offset:128
	global_load_dwordx4 v[126:129], v[172:173], off offset:192
	global_load_dwordx4 v[130:133], v[172:173], off offset:128
	global_load_dwordx4 v[64:67], v[164:165], off offset:192
	s_nop 0
	global_load_dwordx4 v[164:167], v[164:165], off offset:128
	s_waitcnt vmcnt(1)
	v_pk_fma_f32 v[58:59], v[58:59], v[66:67], v[76:77]
	s_waitcnt vmcnt(0)
	v_pk_fma_f32 v[62:63], v[62:63], v[166:167], v[84:85]
	v_pk_fma_f32 v[60:61], v[60:61], v[164:165], v[82:83]
	v_pk_fma_f32 v[54:55], v[54:55], v[166:167], v[110:111]
	v_pk_fma_f32 v[52:53], v[52:53], v[164:165], v[108:109]
	v_pk_fma_f32 v[46:47], v[46:47], v[166:167], v[124:125]
	v_pk_fma_f32 v[44:45], v[44:45], v[164:165], v[122:123]
	v_pk_fma_f32 v[38:39], v[38:39], v[166:167], v[132:133]
	v_pk_fma_f32 v[36:37], v[36:37], v[164:165], v[130:131]
	v_pk_fma_f32 v[56:57], v[56:57], v[64:65], v[74:75]
	global_store_dwordx4 v[120:121], v[60:63], off offset:128
	global_store_dwordx4 v[120:121], v[56:59], off offset:192
	v_pk_fma_f32 v[50:51], v[50:51], v[66:67], v[92:93]
	v_pk_fma_f32 v[48:49], v[48:49], v[64:65], v[90:91]
	global_store_dwordx4 v[112:113], v[52:55], off offset:128
	global_store_dwordx4 v[112:113], v[48:51], off offset:192
	v_pk_fma_f32 v[42:43], v[42:43], v[66:67], v[116:117]
	v_pk_fma_f32 v[40:41], v[40:41], v[64:65], v[114:115]
	global_store_dwordx4 v[104:105], v[44:47], off offset:128
	global_store_dwordx4 v[104:105], v[40:43], off offset:192
	v_pk_fma_f32 v[34:35], v[34:35], v[66:67], v[128:129]
	v_pk_fma_f32 v[32:33], v[32:33], v[64:65], v[126:127]
	global_store_dwordx4 v[96:97], v[36:39], off offset:128
	global_store_dwordx4 v[96:97], v[32:35], off offset:192
	global_load_dwordx4 v[32:35], v[98:99], off offset:192
	s_nop 0
	global_load_dwordx4 v[36:39], v[98:99], off offset:128
	global_load_dwordx4 v[40:43], v[100:101], off offset:192
	global_load_dwordx4 v[44:47], v[100:101], off offset:128
	global_load_dwordx4 v[48:51], v[102:103], off offset:192
	global_load_dwordx4 v[52:55], v[102:103], off offset:128
	global_load_dwordx4 v[56:59], v[106:107], off offset:192
	global_load_dwordx4 v[60:63], v[106:107], off offset:128
	s_waitcnt vmcnt(7)
	v_pk_fma_f32 v[26:27], v[26:27], v[66:67], v[34:35]
	s_waitcnt vmcnt(6)
	v_pk_fma_f32 v[30:31], v[30:31], v[166:167], v[38:39]
	v_pk_fma_f32 v[28:29], v[28:29], v[164:165], v[36:37]
	s_waitcnt vmcnt(4)
	v_pk_fma_f32 v[22:23], v[22:23], v[166:167], v[46:47]
	v_pk_fma_f32 v[20:21], v[20:21], v[164:165], v[44:45]
	s_waitcnt vmcnt(2)
	v_pk_fma_f32 v[14:15], v[14:15], v[166:167], v[54:55]
	v_pk_fma_f32 v[12:13], v[12:13], v[164:165], v[52:53]
	s_waitcnt vmcnt(0)
	v_pk_fma_f32 v[6:7], v[6:7], v[166:167], v[62:63]
	v_pk_fma_f32 v[4:5], v[4:5], v[164:165], v[60:61]
	v_pk_fma_f32 v[24:25], v[24:25], v[64:65], v[32:33]
	global_store_dwordx4 v[88:89], v[28:31], off offset:128
	global_store_dwordx4 v[88:89], v[24:27], off offset:192
	v_pk_fma_f32 v[18:19], v[18:19], v[66:67], v[42:43]
	v_pk_fma_f32 v[16:17], v[16:17], v[64:65], v[40:41]
	global_store_dwordx4 v[80:81], v[20:23], off offset:128
	global_store_dwordx4 v[80:81], v[16:19], off offset:192
	v_pk_fma_f32 v[10:11], v[10:11], v[66:67], v[50:51]
	v_pk_fma_f32 v[8:9], v[8:9], v[64:65], v[48:49]
	global_store_dwordx4 v[72:73], v[12:15], off offset:128
	global_store_dwordx4 v[72:73], v[8:11], off offset:192
	v_pk_fma_f32 v[2:3], v[2:3], v[66:67], v[58:59]
	v_pk_fma_f32 v[0:1], v[0:1], v[64:65], v[56:57]
	global_store_dwordx4 v[68:69], v[4:7], off offset:128
	global_store_dwordx4 v[68:69], v[0:3], off offset:192
	s_cbranch_vccnz .LBB0_98
	v_readlane_b32 s4, v252, 32
	v_readlane_b32 s5, v252, 33
	s_andn2_b64 vcc, exec, s[4:5]
	s_cbranch_vccnz .LBB0_97
	s_barrier
	s_branch .LBB0_97
